# lambda dot products: each wave fetches the four 256-B vectors once (lane = element), LDS broadcast, same fma order (was 64 same-address wave loads per wave in 8 serial round trips); GEMM setprio flips
# baseline (speedup 1.0000x reference)
; __global__ void __launch_bounds__(NTHREADS) fwd_megakernel(Args a) {
;     ...
;         float d1 = 0.f, d2 = 0.f;
;         for (int i = 0; i < 64; ++i) { d1 += a.lq1[i] * a.lk1[i]; d2 += a.lq2[i] * a.lk2[i]; }
.LBB0_687:
	v_and_b32_e32 v3, 63, v160
	v_readfirstlane_b32 s4, v160
	v_lshlrev_b32_e32 v3, 2, v3
	global_load_dword v134, v3, s[80:81]
	global_load_dword v135, v3, s[82:83]
	global_load_dword v136, v3, s[52:53]
	global_load_dword v137, v3, s[54:55]
	s_lshr_b32 s4, s4, 6
	s_lshl_b32 s4, s4, 10
	v_add_u32_e32 v132, s4, v3
	v_mov_b32_e32 v133, s4
	s_waitcnt vmcnt(3)
	ds_write_b32 v132, v134 offset:0
	s_waitcnt vmcnt(2)
	ds_write_b32 v132, v135 offset:256
	s_waitcnt vmcnt(1)
	ds_write_b32 v132, v136 offset:512
	s_waitcnt vmcnt(0)
	ds_write_b32 v132, v137 offset:768
	s_waitcnt lgkmcnt(0)
	ds_read_b128 v[4:7], v133 offset:0
	ds_read_b128 v[8:11], v133 offset:16
	ds_read_b128 v[12:15], v133 offset:32
	ds_read_b128 v[16:19], v133 offset:48
	ds_read_b128 v[20:23], v133 offset:64
	ds_read_b128 v[24:27], v133 offset:80
	ds_read_b128 v[28:31], v133 offset:96
	ds_read_b128 v[32:35], v133 offset:112
	ds_read_b128 v[36:39], v133 offset:256
	ds_read_b128 v[40:43], v133 offset:272
	ds_read_b128 v[44:47], v133 offset:288
	ds_read_b128 v[48:51], v133 offset:304
	ds_read_b128 v[52:55], v133 offset:320
	ds_read_b128 v[56:59], v133 offset:336
	ds_read_b128 v[60:63], v133 offset:352
	ds_read_b128 v[64:67], v133 offset:368
	ds_read_b128 v[68:71], v133 offset:512
	ds_read_b128 v[72:75], v133 offset:528
	ds_read_b128 v[76:79], v133 offset:544
	ds_read_b128 v[80:83], v133 offset:560
	ds_read_b128 v[84:87], v133 offset:576
	ds_read_b128 v[88:91], v133 offset:592
	ds_read_b128 v[92:95], v133 offset:608
	ds_read_b128 v[96:99], v133 offset:624
	ds_read_b128 v[100:103], v133 offset:768
	ds_read_b128 v[104:107], v133 offset:784
	ds_read_b128 v[108:111], v133 offset:800
	ds_read_b128 v[112:115], v133 offset:816
	ds_read_b128 v[116:119], v133 offset:832
	ds_read_b128 v[120:123], v133 offset:848
	ds_read_b128 v[124:127], v133 offset:864
	ds_read_b128 v[128:131], v133 offset:880
	s_waitcnt lgkmcnt(0)
	v_fma_f32 v0, v4, v36, v0
	v_fma_f32 v1, v68, v100, v1
	v_fma_f32 v0, v5, v37, v0
	v_fma_f32 v1, v69, v101, v1
	v_fma_f32 v0, v6, v38, v0
	v_fma_f32 v1, v70, v102, v1
	v_fma_f32 v0, v7, v39, v0
	v_fma_f32 v1, v71, v103, v1
	v_fma_f32 v0, v8, v40, v0
	v_fma_f32 v1, v72, v104, v1
	v_fma_f32 v0, v9, v41, v0
	v_fma_f32 v1, v73, v105, v1
	v_fma_f32 v0, v10, v42, v0
	v_fma_f32 v1, v74, v106, v1
	v_fma_f32 v0, v11, v43, v0
	v_fma_f32 v1, v75, v107, v1
	v_fma_f32 v0, v12, v44, v0
	v_fma_f32 v1, v76, v108, v1
	v_fma_f32 v0, v13, v45, v0
	v_fma_f32 v1, v77, v109, v1
	v_fma_f32 v0, v14, v46, v0
	v_fma_f32 v1, v78, v110, v1
	v_fma_f32 v0, v15, v47, v0
	v_fma_f32 v1, v79, v111, v1
	v_fma_f32 v0, v16, v48, v0
	v_fma_f32 v1, v80, v112, v1
	v_fma_f32 v0, v17, v49, v0
	v_fma_f32 v1, v81, v113, v1
	v_fma_f32 v0, v18, v50, v0
	v_fma_f32 v1, v82, v114, v1
	v_fma_f32 v0, v19, v51, v0
	v_fma_f32 v1, v83, v115, v1
	v_fma_f32 v0, v20, v52, v0
	v_fma_f32 v1, v84, v116, v1
	v_fma_f32 v0, v21, v53, v0
	v_fma_f32 v1, v85, v117, v1
	v_fma_f32 v0, v22, v54, v0
	v_fma_f32 v1, v86, v118, v1
	v_fma_f32 v0, v23, v55, v0
	v_fma_f32 v1, v87, v119, v1
	v_fma_f32 v0, v24, v56, v0
	v_fma_f32 v1, v88, v120, v1
	v_fma_f32 v0, v25, v57, v0
	v_fma_f32 v1, v89, v121, v1
	v_fma_f32 v0, v26, v58, v0
	v_fma_f32 v1, v90, v122, v1
	v_fma_f32 v0, v27, v59, v0
	v_fma_f32 v1, v91, v123, v1
	v_fma_f32 v0, v28, v60, v0
	v_fma_f32 v1, v92, v124, v1
	v_fma_f32 v0, v29, v61, v0
	v_fma_f32 v1, v93, v125, v1
	v_fma_f32 v0, v30, v62, v0
	v_fma_f32 v1, v94, v126, v1
	v_fma_f32 v0, v31, v63, v0
	v_fma_f32 v1, v95, v127, v1
	v_fma_f32 v0, v32, v64, v0
	v_fma_f32 v1, v96, v128, v1
	v_fma_f32 v0, v33, v65, v0
	v_fma_f32 v1, v97, v129, v1
	v_fma_f32 v0, v34, v66, v0
	v_fma_f32 v1, v98, v130, v1
	v_fma_f32 v0, v35, v67, v0
	v_fma_f32 v1, v99, v131, v1
	ds_read_b128 v[4:7], v133 offset:128
	ds_read_b128 v[8:11], v133 offset:144
	ds_read_b128 v[12:15], v133 offset:160
	ds_read_b128 v[16:19], v133 offset:176
	ds_read_b128 v[20:23], v133 offset:192
	ds_read_b128 v[24:27], v133 offset:208
	ds_read_b128 v[28:31], v133 offset:224
	ds_read_b128 v[32:35], v133 offset:240
	ds_read_b128 v[36:39], v133 offset:384
	ds_read_b128 v[40:43], v133 offset:400
	ds_read_b128 v[44:47], v133 offset:416
	ds_read_b128 v[48:51], v133 offset:432
	ds_read_b128 v[52:55], v133 offset:448
	ds_read_b128 v[56:59], v133 offset:464
	ds_read_b128 v[60:63], v133 offset:480
	ds_read_b128 v[64:67], v133 offset:496
	ds_read_b128 v[68:71], v133 offset:640
	ds_read_b128 v[72:75], v133 offset:656
	ds_read_b128 v[76:79], v133 offset:672
	ds_read_b128 v[80:83], v133 offset:688
	ds_read_b128 v[84:87], v133 offset:704
	ds_read_b128 v[88:91], v133 offset:720
	ds_read_b128 v[92:95], v133 offset:736
	ds_read_b128 v[96:99], v133 offset:752
	ds_read_b128 v[100:103], v133 offset:896
	ds_read_b128 v[104:107], v133 offset:912
	ds_read_b128 v[108:111], v133 offset:928
	ds_read_b128 v[112:115], v133 offset:944
	ds_read_b128 v[116:119], v133 offset:960
	ds_read_b128 v[120:123], v133 offset:976
	ds_read_b128 v[124:127], v133 offset:992
	ds_read_b128 v[128:131], v133 offset:1008
	s_waitcnt lgkmcnt(0)
	v_fma_f32 v0, v4, v36, v0
	v_fma_f32 v1, v68, v100, v1
	v_fma_f32 v0, v5, v37, v0
	v_fma_f32 v1, v69, v101, v1
	v_fma_f32 v0, v6, v38, v0
	v_fma_f32 v1, v70, v102, v1
	v_fma_f32 v0, v7, v39, v0
	v_fma_f32 v1, v71, v103, v1
	v_fma_f32 v0, v8, v40, v0
	v_fma_f32 v1, v72, v104, v1
	v_fma_f32 v0, v9, v41, v0
	v_fma_f32 v1, v73, v105, v1
	v_fma_f32 v0, v10, v42, v0
	v_fma_f32 v1, v74, v106, v1
	v_fma_f32 v0, v11, v43, v0
	v_fma_f32 v1, v75, v107, v1
	v_fma_f32 v0, v12, v44, v0
	v_fma_f32 v1, v76, v108, v1
	v_fma_f32 v0, v13, v45, v0
	v_fma_f32 v1, v77, v109, v1
	v_fma_f32 v0, v14, v46, v0
	v_fma_f32 v1, v78, v110, v1
	v_fma_f32 v0, v15, v47, v0
	v_fma_f32 v1, v79, v111, v1
	v_fma_f32 v0, v16, v48, v0
	v_fma_f32 v1, v80, v112, v1
	v_fma_f32 v0, v17, v49, v0
	v_fma_f32 v1, v81, v113, v1
	v_fma_f32 v0, v18, v50, v0
	v_fma_f32 v1, v82, v114, v1
	v_fma_f32 v0, v19, v51, v0
	v_fma_f32 v1, v83, v115, v1
	v_fma_f32 v0, v20, v52, v0
	v_fma_f32 v1, v84, v116, v1
	v_fma_f32 v0, v21, v53, v0
	v_fma_f32 v1, v85, v117, v1
	v_fma_f32 v0, v22, v54, v0
	v_fma_f32 v1, v86, v118, v1
	v_fma_f32 v0, v23, v55, v0
	v_fma_f32 v1, v87, v119, v1
	v_fma_f32 v0, v24, v56, v0
	v_fma_f32 v1, v88, v120, v1
	v_fma_f32 v0, v25, v57, v0
	v_fma_f32 v1, v89, v121, v1
	v_fma_f32 v0, v26, v58, v0
	v_fma_f32 v1, v90, v122, v1
	v_fma_f32 v0, v27, v59, v0
	v_fma_f32 v1, v91, v123, v1
	v_fma_f32 v0, v28, v60, v0
	v_fma_f32 v1, v92, v124, v1
	v_fma_f32 v0, v29, v61, v0
	v_fma_f32 v1, v93, v125, v1
	v_fma_f32 v0, v30, v62, v0
	v_fma_f32 v1, v94, v126, v1
	v_fma_f32 v0, v31, v63, v0
	v_fma_f32 v1, v95, v127, v1
	v_fma_f32 v0, v32, v64, v0
	v_fma_f32 v1, v96, v128, v1
	v_fma_f32 v0, v33, v65, v0
	v_fma_f32 v1, v97, v129, v1
	v_fma_f32 v0, v34, v66, v0
	v_fma_f32 v1, v98, v130, v1
	v_fma_f32 v0, v35, v67, v0
	v_fma_f32 v1, v99, v131, v1
	s_add_u32 s21, s30, 0xde00000
	s_addc_u32 s82, s31, 0
	s_cmpk_gt_i32 s2, 0x1ff
	s_cbranch_scc1 .LBB0_745
; __global__ void __launch_bounds__(NTHREADS) fwd_megakernel(Args a) {
;     ...
;         const float lam = expf(d1) - expf(d2) + LAM_INIT;
;         for (int u = vcu; u < NB * 8 * (SEQ / 256); u += G) {
;             const int bh = u >> 5, qb = u & 31;
;             att::attn_unit(bh >> 3, bh & 7, qb, Qb, Kb, Vb, Ob, (bf16_t*)a.out, a.subln, lam, (char*)lds);
	v_mul_f32_e32 v2, 0x3fb8aa3b, v0
	s_mov_b32 s0, 0x3fb8aa3b
	v_rndne_f32_e32 v3, v2
	v_sub_f32_e32 v4, v2, v3
	v_fma_f32 v2, v0, s0, -v2
	v_fmac_f32_e32 v2, 0x32a5705f, v0
	v_add_f32_e32 v2, v4, v2
	v_exp_f32_e32 v2, v2
	v_cvt_i32_f32_e32 v3, v3
	s_mov_b32 s1, 0xc2ce8ed0
	v_cmp_ngt_f32_e32 vcc, s1, v0
	s_mov_b32 s4, 0x42b17218
	v_ldexp_f32 v2, v2, v3
	v_mul_f32_e32 v3, 0x3fb8aa3b, v1
	v_rndne_f32_e32 v4, v3
	v_sub_f32_e32 v5, v3, v4
	v_fma_f32 v3, v1, s0, -v3
	v_fmac_f32_e32 v3, 0x32a5705f, v1
	v_add_f32_e32 v3, v5, v3
	v_exp_f32_e32 v3, v3
	v_cvt_i32_f32_e32 v4, v4
	v_cndmask_b32_e32 v2, 0, v2, vcc
	v_mov_b32_e32 v5, 0x7f800000
	v_cmp_nlt_f32_e32 vcc, s4, v0
	s_add_u32 s16, s30, 0xbc40000
	s_mov_b32 s7, 0
	v_cndmask_b32_e32 v0, v5, v2, vcc
	v_ldexp_f32 v2, v3, v4
	v_cmp_ngt_f32_e32 vcc, s1, v1
	s_addc_u32 s17, s31, 0
	s_lshl_b32 s23, s2, 2
	v_cndmask_b32_e32 v2, 0, v2, vcc
	v_cmp_nlt_f32_e32 vcc, s4, v1
	s_lshl_b32 s46, s90, 2
	v_mov_b32_e32 v167, 0
	v_cndmask_b32_e32 v1, v5, v2, vcc
	v_sub_f32_e32 v0, v0, v1
	v_add_f32_e32 v163, 0x3e4ccccd, v0
	s_mov_b64 s[8:9], 0x20000
	s_mov_b32 s47, 0x4138aa3b
	s_mov_b64 s[10:11], 0x40000
	s_add_i32 s72, 0, 0x10000
	s_mov_b64 s[12:13], 0x20080
	v_mov_b32_e32 v165, 0x358637bd
	s_mov_b32 s73, 0xf800000
	v_mov_b32_e32 v175, 0x260
	s_mov_b32 s74, 0x3f4ccccd
	s_movk_i32 s75, 0x2000
	v_mbcnt_hi_u32_b32 v176, -1, v174
	s_branch .LBB0_691
